# prep tile loads: both float4 loads of a tile in flight before the wait (loop unrolled x2), on top of epilogue wait de-serialization
# speedup vs baseline: 1.0013x; 1.0013x over previous
; __device__ void phase_prep(PP p) {
;     ...
;         for (int e = tid; e < 1024; e += 512) {
;           const int kk = e >> 4, n4 = (e & 15) * 4;
;           float4 v = *(const float4*)(t.src + (long)(t.k0 + kk) * t.N + t.n0 + n4);
;           if (t.scale) { const float sc = t.scale[t.k0 + kk] * t.mul; v.x *= sc; v.y *= sc; v.z *= sc; v.w *= sc; }
;           float* d = tile + kk * 65 + n4;
;           d[0] = v.x; d[1] = v.y; d[2] = v.z; d[3] = v.w;
;         }
.LBB0_603:
.LBB0_604:
	v_ashrrev_i32_e32 v12, 4, v11
	v_add_u32_e32 v6, s8, v12
	v_ashrrev_i32_e32 v7, 31, v6
	v_mul_lo_u32 v4, s52, v7
	v_mul_lo_u32 v5, s53, v6
	v_mad_u64_u32 v[2:3], s[54:55], s52, v6, 0
	v_and_b32_e32 v0, 60, v10
	v_add3_u32 v3, v3, v4, v5
	v_lshl_add_u64 v[2:3], v[2:3], 2, s[4:5]
	v_lshlrev_b32_e32 v0, 2, v0
	v_lshl_add_u64 v[2:3], v[2:3], 0, v[0:1]
	global_load_dwordx4 v[2:5], v[2:3], off
	v_mov_b32_e32 v84, v0
	v_add_u32_e32 v83, 0x200, v11
	v_add_u32_e32 v82, 0x800, v10
	v_ashrrev_i32_e32 v80, 4, v83
	v_add_u32_e32 v78, s8, v80
	v_ashrrev_i32_e32 v79, 31, v78
	v_mul_lo_u32 v76, s52, v79
	v_mul_lo_u32 v77, s53, v78
	v_mad_u64_u32 v[74:75], s[54:55], s52, v78, 0
	v_and_b32_e32 v0, 60, v82
	v_add3_u32 v75, v75, v76, v77
	v_lshl_add_u64 v[74:75], v[74:75], 2, s[4:5]
	v_lshlrev_b32_e32 v0, 2, v0
	v_lshl_add_u64 v[74:75], v[74:75], 0, v[0:1]
	global_load_dwordx4 v[74:77], v[74:75], off
	s_andn2_b64 vcc, exec, s[56:57]
	s_cbranch_vccnz .Lprep_ns_604
	v_lshl_add_u64 v[6:7], v[6:7], 2, s[50:51]
	global_load_dword v6, v[6:7], off
	v_lshl_add_u64 v[78:79], v[78:79], 2, s[50:51]
	global_load_dword v78, v[78:79], off
	s_waitcnt vmcnt(0)
	v_mul_f32_e32 v6, s13, v6
	v_pk_mul_f32 v[2:3], v[2:3], v[6:7] op_sel_hi:[1,0]
	v_pk_mul_f32 v[4:5], v[4:5], v[6:7] op_sel_hi:[1,0]
	v_mul_f32_e32 v78, s13, v78
	v_pk_mul_f32 v[74:75], v[74:75], v[78:79] op_sel_hi:[1,0]
	v_pk_mul_f32 v[76:77], v[76:77], v[78:79] op_sel_hi:[1,0]
.Lprep_ns_604:
	s_waitcnt vmcnt(0)
	v_mul_lo_u32 v78, v80, s75
	v_add3_u32 v0, 0, v78, v0
	ds_write2_b32 v0, v74, v75 offset1:1
	ds_write2_b32 v0, v76, v77 offset0:2 offset1:3
	v_mul_lo_u32 v6, v12, s75
	v_add3_u32 v0, 0, v6, v84
	ds_write2_b32 v0, v2, v3 offset1:1
	ds_write2_b32 v0, v4, v5 offset0:2 offset1:3

; __device__ void phase_prep(PP p) {
;     ...
;           float* d = tile + kk * 65 + n4;
;           d[0] = v.x; d[1] = v.y; d[2] = v.z; d[3] = v.w;
.Lprep_ns_629:
	s_waitcnt vmcnt(0)
	v_mul_lo_u32 v78, v80, s75
	v_add3_u32 v0, 0, v78, v0
	v_add_u32_e32 v78, 0x4100, v0
	v_add_u32_e32 v0, 0x4108, v0
	ds_write2_b32 v0, v76, v77 offset1:1
	ds_write2_b32 v78, v74, v75 offset1:1
	v_mul_lo_u32 v6, v12, s75
	v_add3_u32 v0, 0, v6, v84
	v_add_u32_e32 v6, 0x4100, v0
	v_add_u32_e32 v0, 0x4108, v0
	ds_write2_b32 v0, v4, v5 offset1:1
	ds_write2_b32 v6, v2, v3 offset1:1

; __device__ void phase_prep(PP p) {
;     ...
;           float* d = tile + kk * 65 + n4;
;           d[0] = v.x; d[1] = v.y; d[2] = v.z; d[3] = v.w;
.Lprep_ns_655:
	s_waitcnt vmcnt(0)
	v_mul_lo_u32 v78, v80, s75
	v_add3_u32 v0, 0, v78, v0
	v_add_u32_e32 v78, 0x8200, v0
	v_add_u32_e32 v0, 0x8208, v0
	ds_write2_b32 v0, v76, v77 offset1:1
	ds_write2_b32 v78, v74, v75 offset1:1
	v_mul_lo_u32 v6, v12, s75
	v_add3_u32 v0, 0, v6, v84
	v_add_u32_e32 v6, 0x8200, v0
	v_add_u32_e32 v0, 0x8208, v0
	ds_write2_b32 v0, v4, v5 offset1:1
	ds_write2_b32 v6, v2, v3 offset1:1

; __device__ void phase_prep(PP p) {
;     ...
;         for (int e = tid; e < 1024; e += 512) {
;           const int kk = e >> 4, n4 = (e & 15) * 4;
;           float4 v = *(const float4*)(t.src + (long)(t.k0 + kk) * t.N + t.n0 + n4);
;           if (t.scale) { const float sc = t.scale[t.k0 + kk] * t.mul; v.x *= sc; v.y *= sc; v.z *= sc; v.w *= sc; }
;           float* d = tile + kk * 65 + n4;
;           d[0] = v.x; d[1] = v.y; d[2] = v.z; d[3] = v.w;
;         }
.LBB0_680:
.LBB0_681:
	v_ashrrev_i32_e32 v12, 4, v11
	v_add_u32_e32 v6, s8, v12
	v_ashrrev_i32_e32 v7, 31, v6
	v_mul_lo_u32 v4, s52, v7
	v_mul_lo_u32 v5, s53, v6
	v_mad_u64_u32 v[2:3], s[54:55], s52, v6, 0
	v_and_b32_e32 v0, 60, v10
	v_add3_u32 v3, v3, v4, v5
	v_lshl_add_u64 v[2:3], v[2:3], 2, s[4:5]
	v_lshlrev_b32_e32 v0, 2, v0
	v_lshl_add_u64 v[2:3], v[2:3], 0, v[0:1]
	global_load_dwordx4 v[2:5], v[2:3], off
	v_mov_b32_e32 v84, v0
	v_add_u32_e32 v83, 0x200, v11
	v_add_u32_e32 v82, 0x800, v10
	v_ashrrev_i32_e32 v80, 4, v83
	v_add_u32_e32 v78, s8, v80
	v_ashrrev_i32_e32 v79, 31, v78
	v_mul_lo_u32 v76, s52, v79
	v_mul_lo_u32 v77, s53, v78
	v_mad_u64_u32 v[74:75], s[54:55], s52, v78, 0
	v_and_b32_e32 v0, 60, v82
	v_add3_u32 v75, v75, v76, v77
	v_lshl_add_u64 v[74:75], v[74:75], 2, s[4:5]
	v_lshlrev_b32_e32 v0, 2, v0
	v_lshl_add_u64 v[74:75], v[74:75], 0, v[0:1]
	global_load_dwordx4 v[74:77], v[74:75], off
	s_andn2_b64 vcc, exec, s[56:57]
	s_cbranch_vccnz .Lprep_ns_681
	v_lshl_add_u64 v[6:7], v[6:7], 2, s[50:51]
	global_load_dword v6, v[6:7], off
	v_lshl_add_u64 v[78:79], v[78:79], 2, s[50:51]
	global_load_dword v78, v[78:79], off
	s_waitcnt vmcnt(0)
	v_mul_f32_e32 v6, s31, v6
	v_pk_mul_f32 v[2:3], v[2:3], v[6:7] op_sel_hi:[1,0]
	v_pk_mul_f32 v[4:5], v[4:5], v[6:7] op_sel_hi:[1,0]
	v_mul_f32_e32 v78, s31, v78
	v_pk_mul_f32 v[74:75], v[74:75], v[78:79] op_sel_hi:[1,0]
	v_pk_mul_f32 v[76:77], v[76:77], v[78:79] op_sel_hi:[1,0]
.Lprep_ns_681:
	s_waitcnt vmcnt(0)
	v_mul_lo_u32 v78, v80, s75
	v_add3_u32 v0, 0, v78, v0
	v_add_u32_e32 v78, 0xc300, v0
	v_add_u32_e32 v0, 0xc308, v0
	ds_write2_b32 v0, v76, v77 offset1:1
	ds_write2_b32 v78, v74, v75 offset1:1
	v_mul_lo_u32 v6, v12, s75
	v_add3_u32 v0, 0, v6, v84
	v_add_u32_e32 v6, 0xc300, v0
	v_add_u32_e32 v0, 0xc308, v0
	ds_write2_b32 v0, v4, v5 offset1:1
	ds_write2_b32 v6, v2, v3 offset1:1

; __device__ void phase_prep(PP p) {
;     ...
;         for (int e = tid; e < 1024; e += 512) {
;           const int kk = e >> 4, n4 = (e & 15) * 4;
;           float4 v = *(const float4*)(t.src + (long)(t.k0 + kk) * t.N + t.n0 + n4);
;           if (t.scale) { const float sc = t.scale[t.k0 + kk] * t.mul; v.x *= sc; v.y *= sc; v.z *= sc; v.w *= sc; }
;           float* d = tile + kk * 65 + n4;
;           d[0] = v.x; d[1] = v.y; d[2] = v.z; d[3] = v.w;
;         }
.LBB0_706:
.LBB0_707:
	v_ashrrev_i32_e32 v12, 4, v11
	v_add_u32_e32 v6, s8, v12
	v_ashrrev_i32_e32 v7, 31, v6
	v_mul_lo_u32 v4, s52, v7
	v_mul_lo_u32 v5, s53, v6
	v_mad_u64_u32 v[2:3], s[54:55], s52, v6, 0
	v_and_b32_e32 v0, 60, v10
	v_add3_u32 v3, v3, v4, v5
	v_lshl_add_u64 v[2:3], v[2:3], 2, s[4:5]
	v_lshlrev_b32_e32 v0, 2, v0
	v_lshl_add_u64 v[2:3], v[2:3], 0, v[0:1]
	global_load_dwordx4 v[2:5], v[2:3], off
	v_mov_b32_e32 v84, v0
	v_add_u32_e32 v83, 0x200, v11
	v_add_u32_e32 v82, 0x800, v10
	v_ashrrev_i32_e32 v80, 4, v83
	v_add_u32_e32 v78, s8, v80
	v_ashrrev_i32_e32 v79, 31, v78
	v_mul_lo_u32 v76, s52, v79
	v_mul_lo_u32 v77, s53, v78
	v_mad_u64_u32 v[74:75], s[54:55], s52, v78, 0
	v_and_b32_e32 v0, 60, v82
	v_add3_u32 v75, v75, v76, v77
	v_lshl_add_u64 v[74:75], v[74:75], 2, s[4:5]
	v_lshlrev_b32_e32 v0, 2, v0
	v_lshl_add_u64 v[74:75], v[74:75], 0, v[0:1]
	global_load_dwordx4 v[74:77], v[74:75], off
	s_andn2_b64 vcc, exec, s[84:85]
	s_cbranch_vccnz .Lprep_ns_707
	v_lshl_add_u64 v[6:7], v[6:7], 2, s[50:51]
	global_load_dword v6, v[6:7], off
	v_lshl_add_u64 v[78:79], v[78:79], 2, s[50:51]
	global_load_dword v78, v[78:79], off
	s_waitcnt vmcnt(0)
	v_mul_f32_e32 v6, s31, v6
	v_pk_mul_f32 v[2:3], v[2:3], v[6:7] op_sel_hi:[1,0]
	v_pk_mul_f32 v[4:5], v[4:5], v[6:7] op_sel_hi:[1,0]
	v_mul_f32_e32 v78, s31, v78
	v_pk_mul_f32 v[74:75], v[74:75], v[78:79] op_sel_hi:[1,0]
	v_pk_mul_f32 v[76:77], v[76:77], v[78:79] op_sel_hi:[1,0]
.Lprep_ns_707:
	s_waitcnt vmcnt(0)
	v_mul_lo_u32 v78, v80, s75
	v_add3_u32 v0, s63, v78, v0
	ds_write2_b32 v0, v74, v75 offset1:1
	ds_write2_b32 v0, v76, v77 offset0:2 offset1:3
	v_mul_lo_u32 v6, v12, s75
	v_add3_u32 v0, s63, v6, v84
	ds_write2_b32 v0, v2, v3 offset1:1
	ds_write2_b32 v0, v4, v5 offset0:2 offset1:3

; __device__ void phase_prep(PP p) {
;     ...
;         for (int e = tid; e < 1024; e += 512) {
;           const int kk = e >> 4, n4 = (e & 15) * 4;
;           float4 v = *(const float4*)(t.src + (long)(t.k0 + kk) * t.N + t.n0 + n4);
;           if (t.scale) { const float sc = t.scale[t.k0 + kk] * t.mul; v.x *= sc; v.y *= sc; v.z *= sc; v.w *= sc; }
;           float* d = tile + kk * 65 + n4;
;           d[0] = v.x; d[1] = v.y; d[2] = v.z; d[3] = v.w;
;         }
.LBB0_732:
.LBB0_733:
	v_ashrrev_i32_e32 v12, 4, v11
	v_add_u32_e32 v6, s8, v12
	v_ashrrev_i32_e32 v7, 31, v6
	v_mul_lo_u32 v4, s84, v7
	v_mul_lo_u32 v5, s85, v6
	v_mad_u64_u32 v[2:3], s[54:55], s84, v6, 0
	v_and_b32_e32 v0, 60, v10
	v_add3_u32 v3, v3, v4, v5
	v_lshl_add_u64 v[2:3], v[2:3], 2, s[4:5]
	v_lshlrev_b32_e32 v0, 2, v0
	v_lshl_add_u64 v[2:3], v[2:3], 0, v[0:1]
	global_load_dwordx4 v[2:5], v[2:3], off
	v_mov_b32_e32 v84, v0
	v_add_u32_e32 v83, 0x200, v11
	v_add_u32_e32 v82, 0x800, v10
	v_ashrrev_i32_e32 v80, 4, v83
	v_add_u32_e32 v78, s8, v80
	v_ashrrev_i32_e32 v79, 31, v78
	v_mul_lo_u32 v76, s84, v79
	v_mul_lo_u32 v77, s85, v78
	v_mad_u64_u32 v[74:75], s[54:55], s84, v78, 0
	v_and_b32_e32 v0, 60, v82
	v_add3_u32 v75, v75, v76, v77
	v_lshl_add_u64 v[74:75], v[74:75], 2, s[4:5]
	v_lshlrev_b32_e32 v0, 2, v0
	v_lshl_add_u64 v[74:75], v[74:75], 0, v[0:1]
	global_load_dwordx4 v[74:77], v[74:75], off
	s_andn2_b64 vcc, exec, s[88:89]
	s_cbranch_vccnz .Lprep_ns_733
	v_lshl_add_u64 v[6:7], v[6:7], 2, s[50:51]
	global_load_dword v6, v[6:7], off
	v_lshl_add_u64 v[78:79], v[78:79], 2, s[50:51]
	global_load_dword v78, v[78:79], off
	s_waitcnt vmcnt(0)
	v_mul_f32_e32 v6, s31, v6
	v_pk_mul_f32 v[2:3], v[2:3], v[6:7] op_sel_hi:[1,0]
	v_pk_mul_f32 v[4:5], v[4:5], v[6:7] op_sel_hi:[1,0]
	v_mul_f32_e32 v78, s31, v78
	v_pk_mul_f32 v[74:75], v[74:75], v[78:79] op_sel_hi:[1,0]
	v_pk_mul_f32 v[76:77], v[76:77], v[78:79] op_sel_hi:[1,0]
.Lprep_ns_733:
	s_waitcnt vmcnt(0)
	v_mul_lo_u32 v78, v80, s75
	v_add3_u32 v0, s62, v78, v0
	ds_write2_b32 v0, v74, v75 offset1:1
	ds_write2_b32 v0, v76, v77 offset0:2 offset1:3
	v_mul_lo_u32 v6, v12, s75
	v_add3_u32 v0, s62, v6, v84
	ds_write2_b32 v0, v2, v3 offset1:1
	ds_write2_b32 v0, v4, v5 offset0:2 offset1:3

; __device__ void phase_prep(PP p) {
;     ...
;         for (int e = tid; e < 1024; e += 512) {
;           const int kk = e >> 4, n4 = (e & 15) * 4;
;           float4 v = *(const float4*)(t.src + (long)(t.k0 + kk) * t.N + t.n0 + n4);
;           if (t.scale) { const float sc = t.scale[t.k0 + kk] * t.mul; v.x *= sc; v.y *= sc; v.z *= sc; v.w *= sc; }
;           float* d = tile + kk * 65 + n4;
;           d[0] = v.x; d[1] = v.y; d[2] = v.z; d[3] = v.w;
;         }
.LBB0_758:
.LBB0_759:
	v_ashrrev_i32_e32 v12, 4, v11
	v_add_u32_e32 v6, s8, v12
	v_ashrrev_i32_e32 v7, 31, v6
	v_mul_lo_u32 v4, s88, v7
	v_mul_lo_u32 v5, s89, v6
	v_mad_u64_u32 v[2:3], s[54:55], s88, v6, 0
	v_and_b32_e32 v0, 60, v10
	v_add3_u32 v3, v3, v4, v5
	v_lshl_add_u64 v[2:3], v[2:3], 2, s[4:5]
	v_lshlrev_b32_e32 v0, 2, v0
	v_lshl_add_u64 v[2:3], v[2:3], 0, v[0:1]
	global_load_dwordx4 v[2:5], v[2:3], off
	v_mov_b32_e32 v84, v0
	v_add_u32_e32 v83, 0x200, v11
	v_add_u32_e32 v82, 0x800, v10
	v_ashrrev_i32_e32 v80, 4, v83
	v_add_u32_e32 v78, s8, v80
	v_ashrrev_i32_e32 v79, 31, v78
	v_mul_lo_u32 v76, s88, v79
	v_mul_lo_u32 v77, s89, v78
	v_mad_u64_u32 v[74:75], s[54:55], s88, v78, 0
	v_and_b32_e32 v0, 60, v82
	v_add3_u32 v75, v75, v76, v77
	v_lshl_add_u64 v[74:75], v[74:75], 2, s[4:5]
	v_lshlrev_b32_e32 v0, 2, v0
	v_lshl_add_u64 v[74:75], v[74:75], 0, v[0:1]
	global_load_dwordx4 v[74:77], v[74:75], off
	s_andn2_b64 vcc, exec, s[94:95]
	s_cbranch_vccnz .Lprep_ns_759
	v_lshl_add_u64 v[6:7], v[6:7], 2, s[84:85]
	global_load_dword v6, v[6:7], off
	v_lshl_add_u64 v[78:79], v[78:79], 2, s[84:85]
	global_load_dword v78, v[78:79], off
	s_waitcnt vmcnt(0)
	v_mul_f32_e32 v6, s31, v6
	v_pk_mul_f32 v[2:3], v[2:3], v[6:7] op_sel_hi:[1,0]
	v_pk_mul_f32 v[4:5], v[4:5], v[6:7] op_sel_hi:[1,0]
	v_mul_f32_e32 v78, s31, v78
	v_pk_mul_f32 v[74:75], v[74:75], v[78:79] op_sel_hi:[1,0]
	v_pk_mul_f32 v[76:77], v[76:77], v[78:79] op_sel_hi:[1,0]
.Lprep_ns_759:
	s_waitcnt vmcnt(0)
	v_mul_lo_u32 v78, v80, s75
	v_add3_u32 v0, s33, v78, v0
	ds_write2_b32 v0, v74, v75 offset1:1
	ds_write2_b32 v0, v76, v77 offset0:2 offset1:3
	v_mul_lo_u32 v6, v12, s75
	v_add3_u32 v0, s33, v6, v84
	ds_write2_b32 v0, v2, v3 offset1:1
	ds_write2_b32 v0, v4, v5 offset0:2 offset1:3

; __device__ void phase_prep(PP p) {
;     ...
;         for (int e = tid; e < 1024; e += 512) {
;           const int kk = e >> 4, n4 = (e & 15) * 4;
;           float4 v = *(const float4*)(t.src + (long)(t.k0 + kk) * t.N + t.n0 + n4);
;           if (t.scale) { const float sc = t.scale[t.k0 + kk] * t.mul; v.x *= sc; v.y *= sc; v.z *= sc; v.w *= sc; }
;           float* d = tile + kk * 65 + n4;
;           d[0] = v.x; d[1] = v.y; d[2] = v.z; d[3] = v.w;
;         }
.LBB0_784:
.LBB0_785:
	v_ashrrev_i32_e32 v12, 4, v11
	v_add_u32_e32 v6, s31, v12
	v_ashrrev_i32_e32 v7, 31, v6
	v_mul_lo_u32 v4, s94, v7
	v_mul_lo_u32 v5, s95, v6
	v_mad_u64_u32 v[2:3], s[54:55], s94, v6, 0
	v_and_b32_e32 v0, 60, v10
	v_add3_u32 v3, v3, v4, v5
	v_lshl_add_u64 v[2:3], v[2:3], 2, s[82:83]
	v_lshlrev_b32_e32 v0, 2, v0
	v_lshl_add_u64 v[2:3], v[2:3], 0, v[0:1]
	global_load_dwordx4 v[2:5], v[2:3], off
	v_mov_b32_e32 v84, v0
	v_add_u32_e32 v83, 0x200, v11
	v_add_u32_e32 v82, 0x800, v10
	v_ashrrev_i32_e32 v80, 4, v83
	v_add_u32_e32 v78, s31, v80
	v_ashrrev_i32_e32 v79, 31, v78
	v_mul_lo_u32 v76, s94, v79
	v_mul_lo_u32 v77, s95, v78
	v_mad_u64_u32 v[74:75], s[54:55], s94, v78, 0
	v_and_b32_e32 v0, 60, v82
	v_add3_u32 v75, v75, v76, v77
	v_lshl_add_u64 v[74:75], v[74:75], 2, s[82:83]
	v_lshlrev_b32_e32 v0, 2, v0
	v_lshl_add_u64 v[74:75], v[74:75], 0, v[0:1]
	global_load_dwordx4 v[74:77], v[74:75], off
	s_andn2_b64 vcc, exec, s[70:71]
	s_cbranch_vccnz .Lprep_ns_785
	v_lshl_add_u64 v[6:7], v[6:7], 2, s[88:89]
	global_load_dword v6, v[6:7], off
	v_lshl_add_u64 v[78:79], v[78:79], 2, s[88:89]
	global_load_dword v78, v[78:79], off
	s_waitcnt vmcnt(0)
	v_mul_f32_e32 v6, s92, v6
	v_pk_mul_f32 v[2:3], v[2:3], v[6:7] op_sel_hi:[1,0]
	v_pk_mul_f32 v[4:5], v[4:5], v[6:7] op_sel_hi:[1,0]
	v_mul_f32_e32 v78, s92, v78
	v_pk_mul_f32 v[74:75], v[74:75], v[78:79] op_sel_hi:[1,0]
	v_pk_mul_f32 v[76:77], v[76:77], v[78:79] op_sel_hi:[1,0]
.Lprep_ns_785:
	s_waitcnt vmcnt(0)
	v_mul_lo_u32 v78, v80, s75
	v_add3_u32 v0, s77, v78, v0
	ds_write2_b32 v0, v74, v75 offset1:1
	ds_write2_b32 v0, v76, v77 offset0:2 offset1:3
	v_mul_lo_u32 v6, v12, s75
	v_add3_u32 v0, s77, v6, v84
	ds_write2_b32 v0, v2, v3 offset1:1
	ds_write2_b32 v0, v4, v5 offset0:2 offset1:3
